# ring combine consumer: the step's 12 ds_reads stay in flight under split_frag; wait + slot release moved to just before the first MFMA
# speedup vs baseline: 1.0150x; 1.0015x over previous
.LBB0_453:
	s_or_b64 exec, exec, s[4:5]
	v_cvt_pk_bf16_f32 v68, v68, v69
	v_cvt_pk_bf16_f32 v69, v70, v71
	v_cvt_pk_bf16_f32 v70, v12, v13
	v_cvt_pk_bf16_f32 v71, v14, v15
	v_lshlrev_b32_e32 v76, 16, v70
	v_and_b32_e32 v77, 0xffff0000, v70
	v_lshlrev_b32_e32 v78, 16, v71
	v_and_b32_e32 v79, 0xffff0000, v71
	v_lshlrev_b32_e32 v72, 16, v68
	v_and_b32_e32 v73, 0xffff0000, v68
	v_lshlrev_b32_e32 v74, 16, v69
	v_and_b32_e32 v75, 0xffff0000, v69
	v_sub_f32_e32 v15, v15, v79
	v_sub_f32_e32 v14, v14, v78
	v_sub_f32_e32 v13, v13, v77
	v_sub_f32_e32 v12, v12, v76
	v_cvt_pk_bf16_f32 v76, v4, v5
	v_cvt_pk_bf16_f32 v77, v6, v7
	v_sub_f32_e32 v19, v19, v75
	v_sub_f32_e32 v18, v18, v74
	v_sub_f32_e32 v17, v17, v73
	v_sub_f32_e32 v16, v16, v72
	v_cvt_pk_bf16_f32 v74, v12, v13
	v_cvt_pk_bf16_f32 v75, v14, v15
	v_cvt_pk_bf16_f32 v78, v8, v9
	v_cvt_pk_bf16_f32 v79, v10, v11
	v_lshlrev_b32_e32 v12, 16, v76
	v_and_b32_e32 v13, 0xffff0000, v76
	v_lshlrev_b32_e32 v14, 16, v77
	v_and_b32_e32 v15, 0xffff0000, v77
	v_cvt_pk_bf16_f32 v72, v16, v17
	v_cvt_pk_bf16_f32 v73, v18, v19
	v_lshlrev_b32_e32 v16, 16, v78
	v_and_b32_e32 v17, 0xffff0000, v78
	v_lshlrev_b32_e32 v18, 16, v79
	v_sub_f32_e32 v7, v7, v15
	v_sub_f32_e32 v6, v6, v14
	v_sub_f32_e32 v5, v5, v13
	v_sub_f32_e32 v4, v4, v12
	v_sub_f32_e32 v12, v10, v18
	v_sub_f32_e32 v10, v9, v17
	v_sub_f32_e32 v13, v8, v16
	v_cvt_pk_bf16_f32 v8, v4, v5
	v_cvt_pk_bf16_f32 v9, v6, v7
	s_waitcnt lgkmcnt(0)
	s_add_i32 s6, s41, 2
	v_mov_b32_e32 v82, s0
	v_mov_b32_e32 v84, s6
	s_and_b64 exec, exec, s[38:39]
	ds_write_b32 v82, v84
	s_mov_b64 exec, -1
	v_mfma_f32_16x16x32_bf16 v[4:7], v[60:63], v[68:71], v[64:67]
	v_and_b32_e32 v19, 0xffff0000, v79
	v_sub_f32_e32 v11, v11, v19
	v_cvt_pk_bf16_f32 v10, v13, v10
	v_mfma_f32_16x16x32_bf16 v[4:7], v[60:63], v[72:75], v[4:7]
	v_cvt_pk_bf16_f32 v11, v12, v11
	s_add_i32 s40, s40, 1
	s_lshl_b32 s96, s40, 12
	v_mfma_f32_16x16x32_bf16 v[4:7], v[28:31], v[76:79], v[4:7]
	s_cmp_eq_u32 s40, 63
	v_mfma_f32_16x16x32_bf16 v[16:19], v[28:31], v[8:11], v[4:7]
	v_mfma_f32_16x16x32_bf16 v[4:7], v[52:55], v[68:71], v[48:51]
	v_mfma_f32_16x16x32_bf16 v[4:7], v[52:55], v[72:75], v[4:7]
	v_mfma_f32_16x16x32_bf16 v[4:7], v[32:35], v[76:79], v[4:7]
	v_mfma_f32_16x16x32_bf16 v[12:15], v[32:35], v[8:11], v[4:7]
	v_mfma_f32_16x16x32_bf16 v[4:7], v[36:39], v[68:71], v[56:59]
	v_mfma_f32_16x16x32_bf16 v[4:7], v[36:39], v[72:75], v[4:7]
	v_mfma_f32_16x16x32_bf16 v[4:7], v[20:23], v[76:79], v[4:7]
	v_mfma_f32_16x16x32_bf16 v[4:7], v[20:23], v[8:11], v[4:7]
	v_mfma_f32_16x16x32_bf16 v[20:23], v[44:47], v[68:71], v[40:43]
	v_mov_b32_e32 v68, v16
	v_mov_b32_e32 v69, v17
	v_mov_b32_e32 v70, v18
	v_mfma_f32_16x16x32_bf16 v[20:23], v[44:47], v[72:75], v[20:23]
	v_mov_b32_e32 v71, v19
	v_mfma_f32_16x16x32_bf16 v[20:23], v[24:27], v[76:79], v[20:23]
	v_mfma_f32_16x16x32_bf16 v[8:11], v[24:27], v[8:11], v[20:23]
	s_nop 6
	v_lshl_add_u64 v[20:21], s[96:97], 2, v[0:1]
	v_add_co_u32_e32 v22, vcc, s19, v20
	global_store_dwordx4 v[20:21], v[16:19], off
	s_nop 0
	v_addc_co_u32_e32 v23, vcc, 0, v21, vcc
	v_add_co_u32_e32 v20, vcc, s64, v20
	global_store_dwordx4 v[22:23], v[12:15], off offset:-4096
	global_store_dwordx4 v[22:23], v[4:7], off
	v_addc_co_u32_e32 v21, vcc, 0, v21, vcc
	global_store_dwordx4 v[20:21], v[8:11], off
	s_cbranch_scc1 .LBB0_473

.LBB0_471:
	s_or_b64 exec, exec, s[4:5]
	s_mulk_i32 s52, 0x3000
	v_add_u32_e32 v24, s52, v2
	ds_read_b128 v[60:63], v24
	ds_read_b128 v[28:31], v24 offset:1024
	ds_read_b128 v[64:67], v24 offset:8192
	ds_read_b128 v[48:51], v24 offset:9216
	ds_read_b128 v[52:55], v24 offset:2048
	ds_read_b128 v[32:35], v24 offset:3072
	ds_read_b128 v[36:39], v24 offset:4096
	ds_read_b128 v[20:23], v24 offset:5120
	ds_read_b128 v[56:59], v24 offset:10240
	ds_read_b128 v[40:43], v24 offset:11264
	ds_read_b128 v[44:47], v24 offset:6144
	ds_read_b128 v[24:27], v24 offset:7168


	s_branch .LBB0_453
